# dn_l1 step: w@S as full-K 16x16x32 bf16 MFMA slices per wave (no partial-sum exchange, one barrier less); prefetch loads and state snapshot stores issued inside the next section's LDS/MFMA wait
# speedup vs baseline: 1.6956x; 1.0148x over previous
.LBB0_475:
	s_and_b64 vcc, exec, s[0:1]
	s_cbranch_vccz .LBB0_497
	v_readlane_b32 s0, v252, 42
	s_mov_b32 s4, s0
	s_ashr_i32 s5, s0, 31
	s_lshl_b32 s2, s0, 5
	s_lshl_b64 s[18:19], s[4:5], 12
	v_readlane_b32 s24, v250, 5
	s_mul_i32 s14, s30, 0x81
	s_add_u32 s4, s24, s18
	v_readlane_b32 s25, v250, 7
	v_readlane_b32 s1, v252, 43
	s_addc_u32 s5, s25, s19
	s_lshl_b32 s6, s14, 14
	v_writelane_b32 v252, s0, 42
	s_ashr_i32 s3, s2, 31
	s_add_i32 s10, s6, 0x8000
	v_writelane_b32 v252, s1, 43
	s_add_u32 s0, s24, s10
	s_addc_u32 s1, s25, 0
	s_add_u32 s0, s0, s18
	s_addc_u32 s1, s1, s19
	v_readlane_b32 s34, v251, 63
	v_readlane_b32 s35, v250, 0
	s_add_u32 s8, s34, s10
	s_addc_u32 s9, s35, 0
	s_add_u32 s10, s56, s10
	s_mul_i32 s12, s30, 0x204000
	s_addc_u32 s11, s57, 0
	s_add_i32 s16, s12, 0x4000
	s_add_u32 s12, s24, s16
	s_addc_u32 s13, s25, 0
	s_add_u32 s12, s12, s18
	s_addc_u32 s13, s13, s19
	s_add_u32 s20, s34, s16
	s_addc_u32 s21, s35, 0
	s_add_u32 s22, s56, s16
	s_addc_u32 s23, s57, 0
	s_lshl_b32 s33, s14, 2
	v_readlane_b32 s36, v250, 3
	v_readlane_b32 s37, v250, 4
	s_add_u32 s16, s36, s33
	s_addc_u32 s17, s37, 0
	s_add_u32 s24, s24, s6
	s_addc_u32 s25, s25, 0
	s_add_u32 s24, s24, s18
	s_addc_u32 s25, s25, s19
	s_add_u32 s26, s34, s6
	s_addc_u32 s27, s35, 0
	v_mov_b32_e32 v0, v218
	s_add_u32 s18, s56, s6
	s_addc_u32 s19, s57, 0
	v_ashrrev_i32_e32 v1, 31, v0
	s_waitcnt vmcnt(3)
	v_lshlrev_b64 v[2:3], 4, v[0:1]
	v_lshl_add_u64 v[4:5], s[18:19], 0, v[2:3]
	s_movk_i32 s18, 0x2000
	s_waitcnt vmcnt(2)
	v_add_co_u32_e32 v6, vcc, s18, v4
	s_movk_i32 s19, 0x3000
	s_nop 0
	v_addc_co_u32_e32 v7, vcc, 0, v5, vcc
	s_waitcnt lgkmcnt(0)
	global_load_dwordx4 v[32:35], v[6:7], off offset:-4096
	global_load_dwordx4 v[36:39], v[6:7], off
	v_add_co_u32_e32 v6, vcc, s19, v4
	v_mov_b32_e32 v1, s33
	s_nop 0
	v_addc_co_u32_e32 v7, vcc, 0, v5, vcc
	global_load_dwordx4 v[64:67], v[4:5], off
	global_load_dwordx4 v[40:43], v[6:7], off
	v_lshl_add_u64 v[4:5], s[26:27], 0, v[2:3]
	v_add_co_u32_e32 v6, vcc, s18, v4
	s_waitcnt vmcnt(5)
	v_lshlrev_b32_e32 v11, 4, v0
	v_addc_co_u32_e32 v7, vcc, 0, v5, vcc
	global_load_dwordx4 v[48:51], v[6:7], off offset:-4096
	global_load_dwordx4 v[52:55], v[6:7], off
	v_add_co_u32_e32 v6, vcc, s19, v4
	s_movk_i32 s6, 0x110
	s_nop 0
	v_addc_co_u32_e32 v7, vcc, 0, v5, vcc
	global_load_dwordx4 v[44:47], v[4:5], off
	global_load_dwordx4 v[68:71], v[6:7], off
	v_lshl_add_u64 v[4:5], s[24:25], 0, v[2:3]
	v_lshl_add_u64 v[6:7], s[22:23], 0, v[2:3]
	global_load_dwordx4 v[82:85], v[4:5], off
	global_load_dwordx4 v[94:97], v[6:7], off
	v_add_co_u32_e32 v4, vcc, s18, v6
	v_ashrrev_i32_e32 v9, 6, v0
	s_nop 0
	v_addc_co_u32_e32 v5, vcc, 0, v7, vcc
	global_load_dwordx4 v[56:59], v[4:5], off offset:-4096
	global_load_dwordx4 v[60:63], v[4:5], off
	v_add_co_u32_e32 v4, vcc, s19, v6
	v_and_b32_e32 v145, 31, v0
	s_nop 0
	v_addc_co_u32_e32 v5, vcc, 0, v7, vcc
	v_lshl_add_u64 v[6:7], s[20:21], 0, v[2:3]
	global_load_dwordx4 v[72:75], v[4:5], off
	global_load_dwordx4 v[76:79], v[6:7], off
	v_add_co_u32_e32 v4, vcc, s18, v6
	v_bfe_u32 v10, v0, 5, 1
	s_nop 0
	v_addc_co_u32_e32 v5, vcc, 0, v7, vcc
	global_load_dwordx4 v[86:89], v[4:5], off offset:-4096
	global_load_dwordx4 v[90:93], v[4:5], off
	v_add_co_u32_e32 v4, vcc, s19, v6
	v_and_b32_e32 v8, 63, v0
	s_nop 0
	v_addc_co_u32_e32 v5, vcc, 0, v7, vcc
	v_lshl_add_u64 v[6:7], s[12:13], 0, v[2:3]
	global_load_dwordx4 v[106:109], v[4:5], off
	global_load_dwordx4 v[110:113], v[6:7], off
	v_lshl_add_u64 v[4:5], s[10:11], 0, v[2:3]
	v_add_co_u32_e32 v6, vcc, s18, v4
	global_load_dwordx3 v[142:144], v1, s[36:37]
	global_load_dwordx4 v[130:133], v[4:5], off
	v_addc_co_u32_e32 v7, vcc, 0, v5, vcc
	v_add_co_u32_e32 v4, vcc, s19, v4
	global_load_dwordx4 v[98:101], v[6:7], off offset:-4096
	global_load_dwordx4 v[102:105], v[6:7], off
	v_addc_co_u32_e32 v5, vcc, 0, v5, vcc
	v_lshl_add_u64 v[6:7], s[8:9], 0, v[2:3]
	global_load_dwordx4 v[114:117], v[4:5], off
	global_load_dwordx4 v[118:121], v[6:7], off
	v_add_co_u32_e32 v4, vcc, s18, v6
	v_add_u32_e32 v1, 0x100, v0
	s_nop 0
	v_addc_co_u32_e32 v5, vcc, 0, v7, vcc
	global_load_dwordx4 v[122:125], v[4:5], off offset:-4096
	global_load_dwordx4 v[126:129], v[4:5], off
	v_add_co_u32_e32 v4, vcc, s19, v6
	s_movk_i32 s8, 0x90
	s_nop 0
	v_addc_co_u32_e32 v5, vcc, 0, v7, vcc
	v_lshl_add_u64 v[6:7], s[0:1], 0, v[2:3]
	global_load_dwordx4 v[134:137], v[4:5], off
	global_load_dwordx4 v[138:141], v[6:7], off
	v_add_u32_e32 v5, 0x200, v0
	v_lshrrev_b32_e32 v7, 4, v0
	v_and_b32_e32 v4, 0xf0, v11
	v_mad_u64_u32 v[146:147], s[0:1], v7, s6, v[4:5]
	v_lshrrev_b32_e32 v7, 4, v1
	v_add_u32_e32 v6, 0x300, v0
	v_mad_u64_u32 v[148:149], s[0:1], v7, s6, v[4:5]
	v_lshrrev_b32_e32 v7, 4, v5
	v_mad_u64_u32 v[150:151], s[0:1], v7, s6, v[4:5]
	v_lshrrev_b32_e32 v7, 4, v6
	v_mad_u64_u32 v[152:153], s[0:1], v7, s6, v[4:5]
	v_and_b32_e32 v4, 0x70, v11
	v_lshrrev_b32_e32 v1, 3, v1
	v_lshrrev_b32_e32 v7, 3, v0
	v_mad_u64_u32 v[156:157], s[0:1], v1, s8, v[4:5]
	v_lshrrev_b32_e32 v1, 3, v5
	v_mad_u64_u32 v[154:155], s[0:1], v7, s8, v[4:5]
	v_mad_u64_u32 v[158:159], s[0:1], v1, s8, v[4:5]
	v_lshrrev_b32_e32 v1, 3, v6
	v_lshlrev_b32_e32 v7, 5, v9
	v_mad_u64_u32 v[160:161], s[0:1], v1, s8, v[4:5]
	v_and_b32_e32 v4, 0xffffffc0, v0
	v_or_b32_e32 v11, v7, v145
	v_and_or_b32 v7, v7, 32, v145
	v_lshlrev_b32_e32 v171, 12, v9
	v_lshlrev_b32_e32 v172, 9, v10
	v_mul_u32_u24_e32 v1, 0x110, v145
	v_mad_u32_u24 v5, v145, s6, v4
	v_lshlrev_b32_e32 v147, 4, v10
	v_mul_u32_u24_e32 v7, 0x110, v7
	v_and_b32_e32 v0, 0xffffff80, v0
	v_lshl_add_u64 v[166:167], s[4:5], 0, v[2:3]
	s_mul_i32 s6, s30, 0x2b0000
	s_lshl_b64 s[4:5], s[2:3], 2
	v_add3_u32 v149, v7, v0, v147
	v_add3_u32 v151, v1, v0, v147
	s_add_u32 s4, s6, s4
	v_or_b32_e32 v0, v171, v172
	s_addc_u32 s5, 0, s5
	v_ashrrev_i32_e32 v1, 31, v0
	v_lshlrev_b32_e32 v6, 3, v10
	v_lshl_add_u64 v[0:1], v[0:1], 2, s[4:5]
	v_readlane_b32 s40, v252, 13
	v_mul_lo_u32 v11, v11, s8
	v_or_b32_e32 v4, v4, v6
	v_lshlrev_b32_e32 v153, 4, v8
	v_mul_u32_u24_e32 v155, 0x90, v145
	v_and_b32_e32 v7, 0x1000, v171
	v_lshl_or_b32 v0, v145, 2, v0
	v_readlane_b32 s54, v252, 27
	v_readlane_b32 s55, v252, 28
	v_mov_b32_e32 v157, 0
	s_mov_b32 s15, 5
	s_mov_b32 s7, 0
	v_cmp_gt_i32_e32 vcc, 2, v9
	v_cmp_lt_i32_e64 s[0:1], 1, v9
	v_lshl_add_u64 v[162:163], s[56:57], 0, v[2:3]
	v_lshl_add_u64 v[164:165], s[34:35], 0, v[2:3]
	v_lshl_add_u64 v[168:169], s[54:55], 0, v[0:1]
	v_mov_b32_e32 v149, v0
	s_mov_b64 s[8:9], 0
	s_movk_i32 s3, 0x7fff
	s_mov_b32 s12, 0x7060302
	v_add_u32_e32 v159, v5, v6
	v_add_u32_e32 v161, v11, v147
	v_mov_b32_e32 v173, 1
	v_add_u32_e32 v174, v4, v155
	v_add_u32_e32 v175, v153, v7
	v_mov_b32_e32 v0, 0
	v_mov_b32_e32 v1, v157
	v_mov_b32_e32 v2, v157
	v_mov_b32_e32 v3, v157
	v_mov_b32_e32 v4, v157
	v_mov_b32_e32 v5, v157
	v_mov_b32_e32 v6, v157
	v_mov_b32_e32 v7, v157
	v_mov_b32_e32 v8, v157
	v_mov_b32_e32 v9, v157
	v_mov_b32_e32 v10, v157
	v_mov_b32_e32 v11, v157
	v_mov_b32_e32 v12, v157
	v_mov_b32_e32 v13, v157
	s_waitcnt vmcnt(28)
	v_mov_b32_e32 v14, v157
	v_mov_b32_e32 v15, v157
	s_barrier
	v_readlane_b32 s41, v252, 14
	v_readlane_b32 s42, v252, 15
	v_readlane_b32 s43, v252, 16
	v_readlane_b32 s44, v252, 17
	v_readlane_b32 s45, v252, 18
	v_readlane_b32 s46, v252, 19
	v_readlane_b32 s47, v252, 20
	v_readlane_b32 s48, v252, 21
	v_readlane_b32 s49, v252, 22
	v_readlane_b32 s50, v252, 23
	v_readlane_b32 s51, v252, 24
	v_readlane_b32 s52, v252, 25
	v_readlane_b32 s53, v252, 26
	v_readlane_b32 s98, v252, 0
	v_readlane_b32 s99, v252, 1
	s_nop 1
	v_subrev_u32_e32 v188, s98, v162
	v_subrev_u32_e32 v192, s98, v164
	v_subrev_u32_e32 v196, s98, v166
	v_add_u32_e32 v189, 0x1000, v188
	v_add_u32_e32 v193, 0x1000, v192
	v_add_u32_e32 v190, 0x2000, v188
	v_add_u32_e32 v194, 0x2000, v192
	v_add_u32_e32 v191, 0x3000, v188
	v_add_u32_e32 v195, 0x3000, v192
	s_waitcnt vmcnt(20)
	ds_write_b128 v146, v[64:67] offset:24576
	ds_write_b128 v148, v[32:35] offset:24576
	ds_write_b128 v150, v[36:39] offset:24576
	ds_write_b128 v152, v[40:43] offset:24576
	ds_write_b128 v154, v[44:47] offset:41984
	ds_write_b128 v156, v[48:51] offset:41984
	ds_write_b128 v158, v[52:55] offset:41984
	ds_write_b128 v160, v[68:71] offset:41984
	ds_write_b128 v154, v[82:85] offset:60416
	v_and_b32_e32 v202, 15, v218
	v_bfe_u32 v203, v218, 4, 2
	v_lshrrev_b32_e32 v204, 6, v218
	v_mul_u32_u24_e32 v199, 0x110, v202
	v_lshl_add_u32 v199, v203, 4, v199
	v_mul_u32_u24_e32 v198, 0x1100, v204
	v_add_u32_e32 v198, v198, v199
	v_add_u32_e32 v198, 0x6000, v198
	v_mul_u32_u24_e32 v200, 0x90, v202
	v_lshl_add_u32 v200, v204, 5, v200
	v_lshl_add_u32 v200, v203, 3, v200
	v_add_u32_e32 v201, 0x2200, v200
	v_add_u32_e32 v200, 0xec00, v200
	s_branch .LBB0_478
.LBB0_477:
	s_waitcnt vmcnt(10)
	s_waitcnt lgkmcnt(0)
	s_barrier
	s_nop 1
	ds_read_b128 v[16:19], v178 offset:8704
	ds_read_b128 v[20:23], v178 offset:8736
	ds_read_b128 v[24:27], v178 offset:8768
	ds_read_b128 v[28:31], v178 offset:8800
	v_pk_mul_f32 v[14:15], v[144:145], v[14:15] op_sel_hi:[0,1]
	v_pk_mul_f32 v[12:13], v[144:145], v[12:13] op_sel_hi:[0,1]
	v_pk_mul_f32 v[10:11], v[144:145], v[10:11] op_sel_hi:[0,1]
	v_pk_mul_f32 v[8:9], v[144:145], v[8:9] op_sel_hi:[0,1]
	v_pk_mul_f32 v[6:7], v[144:145], v[6:7] op_sel_hi:[0,1]
	v_pk_mul_f32 v[4:5], v[144:145], v[4:5] op_sel_hi:[0,1]
	v_pk_mul_f32 v[2:3], v[144:145], v[2:3] op_sel_hi:[0,1]
	v_pk_mul_f32 v[0:1], v[144:145], v[0:1] op_sel_hi:[0,1]
	s_waitcnt lgkmcnt(3)
	s_nop 0
	v_mfma_f32_32x32x16_bf16 v[0:15], v[118:121], v[16:19], v[0:15]
	s_waitcnt lgkmcnt(2)
	v_mfma_f32_32x32x16_bf16 v[0:15], v[114:117], v[20:23], v[0:15]
	s_waitcnt lgkmcnt(1)
	v_mfma_f32_32x32x16_bf16 v[0:15], v[102:105], v[24:27], v[0:15]
	s_waitcnt lgkmcnt(0)
	v_mfma_f32_32x32x16_bf16 v[0:15], v[98:101], v[28:31], v[0:15]
	ds_write_b128 v146, v[64:67] offset:24576
	ds_write_b128 v148, v[32:35] offset:24576
	ds_write_b128 v150, v[36:39] offset:24576
	ds_write_b128 v152, v[40:43] offset:24576
	ds_write_b128 v154, v[44:47] offset:41984
	ds_write_b128 v156, v[48:51] offset:41984
	ds_write_b128 v158, v[52:55] offset:41984
	ds_write_b128 v160, v[68:71] offset:41984
	ds_write_b128 v154, v[82:85] offset:60416
	s_and_b64 s[4:5], s[10:11], exec
	s_cselect_b32 s10, 0x80, s15
	s_add_i32 s6, s10, s14
	s_lshl_b64 s[20:21], s[6:7], 14
	s_add_u32 s100, s98, s20
	s_addc_u32 s101, s99, s21
	global_load_dwordx4 v[98:101], v189, s[100:101]
	global_load_dwordx4 v[102:105], v190, s[100:101]
	s_ashr_i32 s11, s10, 31
	global_load_dwordx4 v[114:117], v191, s[100:101]
	global_load_dwordx4 v[118:121], v192, s[100:101]
	global_load_dwordx4 v[122:125], v193, s[100:101]
	global_load_dwordx4 v[126:129], v194, s[100:101]
	s_lshl_b64 s[4:5], s[10:11], 2
	s_add_u32 s4, s16, s4
	global_load_dwordx4 v[134:137], v195, s[100:101]
	global_load_dwordx4 v[138:141], v196, s[100:101]
	s_addc_u32 s5, s17, s5
	global_load_dwordx4 v[130:133], v188, s[100:101]
	global_load_dword v144, v157, s[4:5]
	s_add_u32 s8, s8, 0x10000
	s_addc_u32 s9, s9, 0
	s_add_i32 s15, s15, 3
	s_cmp_lg_u32 s8, 0x2b0000
	s_waitcnt vmcnt(20)
	v_mov_b32_e32 v142, v177
	s_cbranch_scc0 .LBB0_496

.Ldnl1_go:
	v_cvt_pk_bf16_f32 v16, v0, v1
	v_cvt_pk_bf16_f32 v17, v2, v3
	v_cvt_pk_bf16_f32 v18, v4, v5
	v_cvt_pk_bf16_f32 v19, v6, v7
	ds_write2_b64 v159, v[16:17], v[18:19] offset1:2
	v_cvt_pk_bf16_f32 v16, v8, v9
	v_cvt_pk_bf16_f32 v17, v10, v11
	v_cvt_pk_bf16_f32 v18, v12, v13
	v_cvt_pk_bf16_f32 v19, v14, v15
	ds_write2_b64 v159, v[16:17], v[18:19] offset0:4 offset1:6
	s_waitcnt lgkmcnt(0)
	s_barrier
	ds_read_b128 v[44:47], v161 offset:41984
	ds_read_b128 v[40:43], v161 offset:42016
	ds_read_b128 v[36:39], v161 offset:42048
	ds_read_b128 v[32:35], v161 offset:42080
	ds_read_b64 v[52:53], v200
	ds_read_b64 v[54:55], v200 offset:2304
	ds_read_b128 v[206:209], v198
	ds_read_b128 v[226:229], v199
	ds_read_b128 v[16:19], v199 offset:4352
	ds_read_b128 v[210:213], v198 offset:64
	ds_read_b128 v[230:233], v199 offset:64
	ds_read_b128 v[20:23], v199 offset:4416
	ds_read_b128 v[214:217], v198 offset:128
	ds_read_b128 v[234:237], v199 offset:128
	ds_read_b128 v[24:27], v199 offset:4480
	v_readlane_b32 s20, v252, 27
	v_readlane_b32 s21, v252, 28
	s_add_u32 s20, s20, s8
	s_addc_u32 s21, s21, 0
	s_add_u32 s20, s20, 0x7489000
	s_addc_u32 s21, s21, 0
	global_store_dword v149, v0, s[20:21] nt
	global_store_dword v149, v1, s[20:21] offset:512 nt
	global_store_dword v149, v2, s[20:21] offset:1024 nt
	global_store_dword v149, v3, s[20:21] offset:1536 nt
	s_waitcnt lgkmcnt(6)
	v_mfma_f32_16x16x32_bf16 v[242:245], v[206:209], v[226:229], 0
	v_mfma_f32_16x16x32_bf16 v[246:249], v[206:209], v[16:19], 0
	ds_read_b128 v[222:225], v198 offset:192
	ds_read_b128 v[238:241], v199 offset:192
	ds_read_b128 v[28:31], v199 offset:4544
	s_add_u32 s20, s20, 0x1000
	s_addc_u32 s21, s21, 0
	global_store_dword v149, v4, s[20:21] nt
	global_store_dword v149, v5, s[20:21] offset:512 nt
	global_store_dword v149, v6, s[20:21] offset:1024 nt
	global_store_dword v149, v7, s[20:21] offset:1536 nt
	s_waitcnt lgkmcnt(6)
	v_mfma_f32_16x16x32_bf16 v[242:245], v[210:213], v[230:233], v[242:245]
	v_mfma_f32_16x16x32_bf16 v[246:249], v[210:213], v[20:23], v[246:249]
	s_add_u32 s20, s20, 0x1000
	s_addc_u32 s21, s21, 0
	global_store_dword v149, v8, s[20:21] nt
	global_store_dword v149, v9, s[20:21] offset:512 nt
	global_store_dword v149, v10, s[20:21] offset:1024 nt
	global_store_dword v149, v11, s[20:21] offset:1536 nt
	s_waitcnt lgkmcnt(3)
	v_mfma_f32_16x16x32_bf16 v[242:245], v[214:217], v[234:237], v[242:245]
	v_mfma_f32_16x16x32_bf16 v[246:249], v[214:217], v[24:27], v[246:249]
	s_add_u32 s20, s20, 0x1000
	s_addc_u32 s21, s21, 0
	global_store_dword v149, v12, s[20:21] nt
	global_store_dword v149, v13, s[20:21] offset:512 nt
	global_store_dword v149, v14, s[20:21] offset:1024 nt
	global_store_dword v149, v15, s[20:21] offset:1536 nt
	s_waitcnt lgkmcnt(0)
	v_mfma_f32_16x16x32_bf16 v[242:245], v[222:225], v[238:241], v[242:245]
	v_mfma_f32_16x16x32_bf16 v[246:249], v[222:225], v[28:31], v[246:249]
	v_lshlrev_b32_e32 v206, 16, v52
	v_and_b32_e32 v207, 0xffff0000, v52
	v_lshlrev_b32_e32 v208, 16, v53
	v_and_b32_e32 v209, 0xffff0000, v53
	v_lshlrev_b32_e32 v210, 16, v54
	v_and_b32_e32 v211, 0xffff0000, v54
	v_lshlrev_b32_e32 v212, 16, v55
	v_and_b32_e32 v213, 0xffff0000, v55
	s_nop 7
	s_nop 1
	v_pk_add_f32 v[206:207], v[206:207], v[242:243] neg_lo:[0,1] neg_hi:[0,1]
	v_pk_add_f32 v[208:209], v[208:209], v[244:245] neg_lo:[0,1] neg_hi:[0,1]
	v_pk_add_f32 v[210:211], v[210:211], v[246:247] neg_lo:[0,1] neg_hi:[0,1]
	v_pk_add_f32 v[212:213], v[212:213], v[248:249] neg_lo:[0,1] neg_hi:[0,1]
	v_cvt_pk_bf16_f32 v206, v206, v207
	v_cvt_pk_bf16_f32 v207, v208, v209
	v_cvt_pk_bf16_f32 v210, v210, v211
	v_cvt_pk_bf16_f32 v211, v212, v213
	ds_write_b64 v201, v[206:207]
	ds_write_b64 v201, v[210:211] offset:2304
	v_add_u32_e32 v176, v153, v171
	v_add_u32_e32 v178, v147, v155
	s_waitcnt lgkmcnt(0)
	s_barrier
	ds_read_b128 v[16:19], v178 offset:8704
	ds_read_b128 v[20:23], v178 offset:8736
	ds_read_b128 v[24:27], v178 offset:8768
	ds_read_b128 v[28:31], v178 offset:8800
	s_waitcnt vmcnt(25)
	v_pk_mul_f32 v[14:15], v[14:15], v[142:143] op_sel_hi:[1,0]
	v_pk_mul_f32 v[12:13], v[12:13], v[142:143] op_sel_hi:[1,0]
	v_pk_mul_f32 v[10:11], v[10:11], v[142:143] op_sel_hi:[1,0]
	v_pk_mul_f32 v[8:9], v[8:9], v[142:143] op_sel_hi:[1,0]
	v_pk_mul_f32 v[6:7], v[6:7], v[142:143] op_sel_hi:[1,0]
	v_pk_mul_f32 v[4:5], v[4:5], v[142:143] op_sel_hi:[1,0]
	v_pk_mul_f32 v[2:3], v[2:3], v[142:143] op_sel_hi:[1,0]
	v_pk_mul_f32 v[0:1], v[0:1], v[142:143] op_sel_hi:[1,0]
	s_waitcnt lgkmcnt(3)
	s_nop 0
	v_mfma_f32_32x32x16_bf16 v[0:15], v[44:47], v[16:19], v[0:15]
	s_waitcnt lgkmcnt(2)
	v_mfma_f32_32x32x16_bf16 v[0:15], v[40:43], v[20:23], v[0:15]
	s_waitcnt lgkmcnt(1)
	v_mfma_f32_32x32x16_bf16 v[0:15], v[36:39], v[24:27], v[0:15]
	s_waitcnt lgkmcnt(0)
	v_mfma_f32_32x32x16_bf16 v[0:15], v[32:35], v[28:31], v[0:15]
	s_waitcnt vmcnt(26)
	ds_write_b128 v146, v[94:97] offset:24576
	ds_write_b128 v148, v[56:59] offset:24576
	ds_write_b128 v150, v[60:63] offset:24576
	ds_write_b128 v152, v[72:75] offset:24576
	ds_write_b128 v154, v[76:79] offset:41984
	ds_write_b128 v156, v[86:89] offset:41984
	ds_write_b128 v158, v[90:93] offset:41984
	ds_write_b128 v160, v[106:109] offset:41984
	ds_write_b128 v154, v[110:113] offset:60416
	v_cvt_pk_bf16_f32 v16, v0, v1
	v_cvt_pk_bf16_f32 v17, v2, v3
	v_cvt_pk_bf16_f32 v18, v4, v5
	v_cvt_pk_bf16_f32 v19, v6, v7
	ds_write2_b64 v159, v[16:17], v[18:19] offset1:2
	v_cvt_pk_bf16_f32 v16, v8, v9
	v_cvt_pk_bf16_f32 v17, v10, v11
	v_cvt_pk_bf16_f32 v18, v12, v13
	v_cvt_pk_bf16_f32 v19, v14, v15
	ds_write2_b64 v159, v[16:17], v[18:19] offset0:4 offset1:6
	s_waitcnt lgkmcnt(0)
	s_barrier
	ds_read_b128 v[76:79], v161 offset:41984
	ds_read_b128 v[72:75], v161 offset:42016
	ds_read_b128 v[60:63], v161 offset:42048
	ds_read_b128 v[56:59], v161 offset:42080
	ds_read_b64 v[90:91], v200
	ds_read_b64 v[92:93], v200 offset:2304
	ds_read_b128 v[206:209], v198
	ds_read_b128 v[226:229], v199
	ds_read_b128 v[16:19], v199 offset:4352
	ds_read_b128 v[210:213], v198 offset:64
	ds_read_b128 v[230:233], v199 offset:64
	ds_read_b128 v[20:23], v199 offset:4416
	ds_read_b128 v[214:217], v198 offset:128
	ds_read_b128 v[234:237], v199 offset:128
	ds_read_b128 v[24:27], v199 offset:4480
	s_add_i32 s6, s15, -2
	s_cmp_eq_u32 s8, 0x2a0000
	s_cselect_b64 s[10:11], -1, 0
	s_and_b64 s[4:5], s[10:11], exec
	s_cselect_b32 s20, 0x80, s6
	s_add_i32 s6, s20, s14
	s_lshl_b64 s[22:23], s[6:7], 14
	s_add_u32 s100, s98, s22
	s_addc_u32 s101, s99, s23
	global_load_dwordx4 v[32:35], v189, s[100:101]
	global_load_dwordx4 v[36:39], v190, s[100:101]
	s_ashr_i32 s21, s20, 31
	global_load_dwordx4 v[40:43], v191, s[100:101]
	global_load_dwordx4 v[44:47], v192, s[100:101]
	s_waitcnt lgkmcnt(6)
	v_mfma_f32_16x16x32_bf16 v[242:245], v[206:209], v[226:229], 0
	v_mfma_f32_16x16x32_bf16 v[246:249], v[206:209], v[16:19], 0
	ds_read_b128 v[222:225], v198 offset:192
	ds_read_b128 v[238:241], v199 offset:192
	ds_read_b128 v[28:31], v199 offset:4544
	global_load_dwordx4 v[48:51], v193, s[100:101]
	global_load_dwordx4 v[52:55], v194, s[100:101]
	s_lshl_b64 s[4:5], s[20:21], 2
	s_add_u32 s4, s16, s4
	global_load_dwordx4 v[68:71], v195, s[100:101]
	s_waitcnt lgkmcnt(6)
	v_mfma_f32_16x16x32_bf16 v[242:245], v[210:213], v[230:233], v[242:245]
	v_mfma_f32_16x16x32_bf16 v[246:249], v[210:213], v[20:23], v[246:249]
	global_load_dwordx4 v[82:85], v196, s[100:101]
	s_addc_u32 s5, s17, s5
	global_load_dwordx4 v[64:67], v188, s[100:101]
	global_load_dword v177, v157, s[4:5]
	s_waitcnt lgkmcnt(3)
	v_mfma_f32_16x16x32_bf16 v[242:245], v[214:217], v[234:237], v[242:245]
	v_mfma_f32_16x16x32_bf16 v[246:249], v[214:217], v[24:27], v[246:249]
	s_waitcnt lgkmcnt(0)
	v_mfma_f32_16x16x32_bf16 v[242:245], v[222:225], v[238:241], v[242:245]
	v_mfma_f32_16x16x32_bf16 v[246:249], v[222:225], v[28:31], v[246:249]
	v_lshlrev_b32_e32 v206, 16, v90
	v_and_b32_e32 v207, 0xffff0000, v90
	v_lshlrev_b32_e32 v208, 16, v91
	v_and_b32_e32 v209, 0xffff0000, v91
	v_lshlrev_b32_e32 v210, 16, v92
	v_and_b32_e32 v211, 0xffff0000, v92
	v_lshlrev_b32_e32 v212, 16, v93
	v_and_b32_e32 v213, 0xffff0000, v93
	s_nop 7
	s_nop 1
	v_pk_add_f32 v[206:207], v[206:207], v[242:243] neg_lo:[0,1] neg_hi:[0,1]
	v_pk_add_f32 v[208:209], v[208:209], v[244:245] neg_lo:[0,1] neg_hi:[0,1]
	v_pk_add_f32 v[210:211], v[210:211], v[246:247] neg_lo:[0,1] neg_hi:[0,1]
	v_pk_add_f32 v[212:213], v[212:213], v[248:249] neg_lo:[0,1] neg_hi:[0,1]
	v_cvt_pk_bf16_f32 v206, v206, v207
	v_cvt_pk_bf16_f32 v207, v208, v209
	v_cvt_pk_bf16_f32 v210, v210, v211
	v_cvt_pk_bf16_f32 v211, v212, v213
	ds_write_b64 v201, v[206:207]
	ds_write_b64 v201, v[210:211] offset:2304
	s_waitcnt lgkmcnt(0)
	s_barrier
	s_nop 1
	ds_read_b128 v[16:19], v178 offset:8704
	ds_read_b128 v[20:23], v178 offset:8736
	ds_read_b128 v[24:27], v178 offset:8768
	ds_read_b128 v[28:31], v178 offset:8800
	v_pk_mul_f32 v[0:1], v[142:143], v[0:1] op_sel:[1,0]
	v_pk_mul_f32 v[14:15], v[142:143], v[14:15] op_sel:[1,0]
	v_pk_mul_f32 v[12:13], v[142:143], v[12:13] op_sel:[1,0]
	v_pk_mul_f32 v[10:11], v[142:143], v[10:11] op_sel:[1,0]
	v_pk_mul_f32 v[8:9], v[142:143], v[8:9] op_sel:[1,0]
	v_pk_mul_f32 v[6:7], v[142:143], v[6:7] op_sel:[1,0]
	v_pk_mul_f32 v[4:5], v[142:143], v[4:5] op_sel:[1,0]
	v_pk_mul_f32 v[2:3], v[142:143], v[2:3] op_sel:[1,0]
	s_waitcnt lgkmcnt(3)
	s_nop 0
	v_mfma_f32_32x32x16_bf16 v[0:15], v[76:79], v[16:19], v[0:15]
	s_waitcnt lgkmcnt(2)
	v_mfma_f32_32x32x16_bf16 v[0:15], v[72:75], v[20:23], v[0:15]
	s_waitcnt lgkmcnt(1)
	v_mfma_f32_32x32x16_bf16 v[0:15], v[60:63], v[24:27], v[0:15]
	s_waitcnt lgkmcnt(0)
	v_mfma_f32_32x32x16_bf16 v[0:15], v[56:59], v[28:31], v[0:15]
	s_waitcnt vmcnt(26)
	ds_write_b128 v146, v[130:133] offset:24576
	ds_write_b128 v148, v[98:101] offset:24576
	ds_write_b128 v150, v[102:105] offset:24576
	ds_write_b128 v152, v[114:117] offset:24576
	ds_write_b128 v154, v[118:121] offset:41984
	ds_write_b128 v156, v[122:125] offset:41984
	ds_write_b128 v158, v[126:129] offset:41984
	ds_write_b128 v160, v[134:137] offset:41984
	ds_write_b128 v154, v[138:141] offset:60416
	v_cvt_pk_bf16_f32 v16, v0, v1
	v_cvt_pk_bf16_f32 v17, v2, v3
	v_cvt_pk_bf16_f32 v18, v4, v5
	v_cvt_pk_bf16_f32 v19, v6, v7
	ds_write2_b64 v159, v[16:17], v[18:19] offset1:2
	v_cvt_pk_bf16_f32 v16, v8, v9
	v_cvt_pk_bf16_f32 v17, v10, v11
	v_cvt_pk_bf16_f32 v18, v12, v13
	v_cvt_pk_bf16_f32 v19, v14, v15
	ds_write2_b64 v159, v[16:17], v[18:19] offset0:4 offset1:6
	s_waitcnt lgkmcnt(0)
	s_barrier
	ds_read_b128 v[118:121], v161 offset:41984
	ds_read_b128 v[114:117], v161 offset:42016
	ds_read_b128 v[102:105], v161 offset:42048
	ds_read_b128 v[98:101], v161 offset:42080
	ds_read_b64 v[126:127], v200
	ds_read_b64 v[128:129], v200 offset:2304
	ds_read_b128 v[206:209], v198
	ds_read_b128 v[226:229], v199
	ds_read_b128 v[16:19], v199 offset:4352
	ds_read_b128 v[210:213], v198 offset:64
	ds_read_b128 v[230:233], v199 offset:64
	ds_read_b128 v[20:23], v199 offset:4416
	ds_read_b128 v[214:217], v198 offset:128
	ds_read_b128 v[234:237], v199 offset:128
	ds_read_b128 v[24:27], v199 offset:4480
	s_add_i32 s6, s15, -1
	s_and_b64 s[4:5], s[10:11], exec
	s_cselect_b32 s20, 0x80, s6
	s_add_i32 s6, s20, s14
	s_lshl_b64 s[22:23], s[6:7], 14
	s_add_u32 s100, s98, s22
	s_addc_u32 s101, s99, s23
	global_load_dwordx4 v[56:59], v189, s[100:101]
	global_load_dwordx4 v[60:63], v190, s[100:101]
	s_ashr_i32 s21, s20, 31
	global_load_dwordx4 v[72:75], v191, s[100:101]
	global_load_dwordx4 v[76:79], v192, s[100:101]
	s_waitcnt lgkmcnt(6)
	v_mfma_f32_16x16x32_bf16 v[242:245], v[206:209], v[226:229], 0
	v_mfma_f32_16x16x32_bf16 v[246:249], v[206:209], v[16:19], 0
	ds_read_b128 v[222:225], v198 offset:192
	ds_read_b128 v[238:241], v199 offset:192
	ds_read_b128 v[28:31], v199 offset:4544
	global_load_dwordx4 v[86:89], v193, s[100:101]
	global_load_dwordx4 v[90:93], v194, s[100:101]
	s_lshl_b64 s[4:5], s[20:21], 2
	s_add_u32 s4, s16, s4
	global_load_dwordx4 v[106:109], v195, s[100:101]
	s_waitcnt lgkmcnt(6)
	v_mfma_f32_16x16x32_bf16 v[242:245], v[210:213], v[230:233], v[242:245]
	v_mfma_f32_16x16x32_bf16 v[246:249], v[210:213], v[20:23], v[246:249]
	global_load_dwordx4 v[110:113], v196, s[100:101]
	s_addc_u32 s5, s17, s5
	global_load_dwordx4 v[94:97], v188, s[100:101]
	global_load_dword v143, v157, s[4:5]
	s_waitcnt lgkmcnt(3)
	v_mfma_f32_16x16x32_bf16 v[242:245], v[214:217], v[234:237], v[242:245]
	v_mfma_f32_16x16x32_bf16 v[246:249], v[214:217], v[24:27], v[246:249]
	s_waitcnt lgkmcnt(0)
	v_mfma_f32_16x16x32_bf16 v[242:245], v[222:225], v[238:241], v[242:245]
	v_mfma_f32_16x16x32_bf16 v[246:249], v[222:225], v[28:31], v[246:249]
	v_lshlrev_b32_e32 v206, 16, v126
	v_and_b32_e32 v207, 0xffff0000, v126
	v_lshlrev_b32_e32 v208, 16, v127
	v_and_b32_e32 v209, 0xffff0000, v127
	v_lshlrev_b32_e32 v210, 16, v128
	v_and_b32_e32 v211, 0xffff0000, v128
	v_lshlrev_b32_e32 v212, 16, v129
	v_and_b32_e32 v213, 0xffff0000, v129
	s_nop 7
	s_nop 1
	v_pk_add_f32 v[206:207], v[206:207], v[242:243] neg_lo:[0,1] neg_hi:[0,1]
	v_pk_add_f32 v[208:209], v[208:209], v[244:245] neg_lo:[0,1] neg_hi:[0,1]
	v_pk_add_f32 v[210:211], v[210:211], v[246:247] neg_lo:[0,1] neg_hi:[0,1]
	v_pk_add_f32 v[212:213], v[212:213], v[248:249] neg_lo:[0,1] neg_hi:[0,1]
	v_cvt_pk_bf16_f32 v206, v206, v207
	v_cvt_pk_bf16_f32 v207, v208, v209
	v_cvt_pk_bf16_f32 v210, v210, v211
	v_cvt_pk_bf16_f32 v211, v212, v213
	ds_write_b64 v201, v[206:207]
	ds_write_b64 v201, v[210:211] offset:2304
	s_branch .LBB0_477
